# diff attention loop: row-max chain trimmed (no x1.0 multiplies, no NaN-canonicalising self-max, dead lane-index math removed)
# speedup vs baseline: 1.0154x; 1.0154x over previous
.LBB0_481:
	s_or_b64 exec, exec, s[0:1]
	s_nop 5
	v_max3_f32 v170, v82, v66, v83
	v_max3_f32 v170, v170, v67, v84
	v_max3_f32 v170, v170, v68, v85
	v_max3_f32 v170, v170, v69, v86
	v_cndmask_b32_e32 v0, 0, v149, vcc
	v_max3_f32 v170, v170, v70, v87
	s_mov_b32 s0, 0x41200000
	v_max3_f32 v170, v170, v71, v88
	s_nop 0
	v_max3_f32 v170, v170, v72, v89
	s_nop 0
	v_max3_f32 v170, v170, v73, v90
	s_nop 0
	v_max3_f32 v170, v170, v74, v91
	s_nop 0
	v_max3_f32 v170, v170, v75, v92
	s_nop 0
	v_max3_f32 v170, v170, v76, v93
	s_nop 0
	v_max3_f32 v170, v170, v77, v94
	s_nop 0
	v_max3_f32 v170, v170, v78, v95
	s_nop 0
	v_max3_f32 v170, v170, v79, v96
	s_nop 0
	v_max3_f32 v170, v170, v80, v97
	s_nop 0
	v_max_f32_e32 v170, v170, v81
	v_mov_b32_e32 v171, v170
	s_nop 1
	v_permlane32_swap_b32_e32 v171, v170
	v_max_f32_e32 v170, v170, v171
	v_add_f32_e32 v170, v0, v170
	v_sub_f32_e32 v171, v170, v150
	v_cmp_lt_f32_e32 vcc, s0, v171
	s_cbranch_vccz .LBB0_483
	v_max_f32_e32 v170, v170, v170
	v_max_f32_e32 v171, v150, v150
	v_max_f32_e32 v170, v171, v170
	v_sub_f32_e32 v150, v150, v170
	v_exp_f32_e32 v150, v150
	s_nop 0
	v_pk_mul_f32 v[64:65], v[64:65], v[150:151] op_sel_hi:[1,0]
	v_pk_mul_f32 v[62:63], v[62:63], v[150:151] op_sel_hi:[1,0]
	v_pk_mul_f32 v[60:61], v[60:61], v[150:151] op_sel_hi:[1,0]
	v_pk_mul_f32 v[58:59], v[58:59], v[150:151] op_sel_hi:[1,0]
	v_pk_mul_f32 v[56:57], v[56:57], v[150:151] op_sel_hi:[1,0]
	v_pk_mul_f32 v[54:55], v[54:55], v[150:151] op_sel_hi:[1,0]
	v_pk_mul_f32 v[52:53], v[52:53], v[150:151] op_sel_hi:[1,0]
	v_pk_mul_f32 v[50:51], v[50:51], v[150:151] op_sel_hi:[1,0]
	v_pk_mul_f32 v[48:49], v[48:49], v[150:151] op_sel_hi:[1,0]
	v_pk_mul_f32 v[46:47], v[46:47], v[150:151] op_sel_hi:[1,0]
	v_pk_mul_f32 v[44:45], v[44:45], v[150:151] op_sel_hi:[1,0]
	v_pk_mul_f32 v[42:43], v[42:43], v[150:151] op_sel_hi:[1,0]
	v_pk_mul_f32 v[40:41], v[40:41], v[150:151] op_sel_hi:[1,0]
	v_pk_mul_f32 v[38:39], v[38:39], v[150:151] op_sel_hi:[1,0]
	v_pk_mul_f32 v[36:37], v[36:37], v[150:151] op_sel_hi:[1,0]
	v_pk_mul_f32 v[34:35], v[34:35], v[150:151] op_sel_hi:[1,0]
	v_pk_mul_f32 v[32:33], v[32:33], v[150:151] op_sel_hi:[1,0]
	v_pk_mul_f32 v[30:31], v[30:31], v[150:151] op_sel_hi:[1,0]
	v_pk_mul_f32 v[28:29], v[28:29], v[150:151] op_sel_hi:[1,0]
	v_pk_mul_f32 v[26:27], v[26:27], v[150:151] op_sel_hi:[1,0]
	v_pk_mul_f32 v[24:25], v[24:25], v[150:151] op_sel_hi:[1,0]
	v_pk_mul_f32 v[22:23], v[22:23], v[150:151] op_sel_hi:[1,0]
	v_pk_mul_f32 v[20:21], v[20:21], v[150:151] op_sel_hi:[1,0]
	v_pk_mul_f32 v[18:19], v[18:19], v[150:151] op_sel_hi:[1,0]
	v_pk_mul_f32 v[16:17], v[16:17], v[150:151] op_sel_hi:[1,0]
	v_pk_mul_f32 v[14:15], v[14:15], v[150:151] op_sel_hi:[1,0]
	v_pk_mul_f32 v[12:13], v[12:13], v[150:151] op_sel_hi:[1,0]
	v_pk_mul_f32 v[10:11], v[10:11], v[150:151] op_sel_hi:[1,0]
	v_pk_mul_f32 v[8:9], v[8:9], v[150:151] op_sel_hi:[1,0]
	v_pk_mul_f32 v[6:7], v[6:7], v[150:151] op_sel_hi:[1,0]
	v_pk_mul_f32 v[4:5], v[4:5], v[150:151] op_sel_hi:[1,0]
	v_pk_mul_f32 v[2:3], v[2:3], v[150:151] op_sel_hi:[1,0]
	v_mul_f32_e32 v131, v131, v150
	v_mov_b32_e32 v150, v170
